# conv LayerNorm sums via DPP/permlane swaps instead of ds_bpermute; sample_gemm unit ids permuted for XCD-local weight reuse; SS loads batched
# speedup vs baseline: 1.0821x; 1.0083x over previous
; template <class EpiS>
; DI void sample_gemm(LAS unsigned char* lds, const bf16_t* A, const bf16_t* Bt, int nN, int K, const EpiS& E) {
;     const int tid = threadIdx.x, lane = tid & 63, w = __builtin_amdgcn_readfirstlane(tid >> 6), r32 = lane & 31, h = lane >> 5;
;     const int nunits = 16 * nN, kw = K >> 3, nk = kw >> 4;
;     for (int un = (int)blockIdx.x; un < nunits; un += (int)gridDim.x) {
;         const int rb = un & 3, wc = (un >> 2) & 3, pn = un >> 4;
;         const bf16_t* ap = A + (size_t)(MP + rb * 32 + r32) * K + w * kw + h * 8;
;         const bf16_t* b0p = Bt + (size_t)(pn * 256 + wc * 32 + r32) * K + w * kw + h * 8;
;         const bf16_t* b1p = b0p + (size_t)128 * K;
.LBB0_336:
	s_cmpk_gt_i32 s2, 0x9f
	v_readfirstlane_b32 s4, v1
	s_cbranch_scc1 .LBB0_351
	v_and_b32_e32 v155, 63, v1
	v_lshrrev_b32_e32 v156, 6, v1
	v_and_b32_e32 v156, 7, v156
	v_lshlrev_b32_e32 v156, 13, v156
	v_add_u32_e32 v156, 0x10000, v156
	v_lshrrev_b32_e32 v182, 3, v155
	v_and_b32_e32 v165, 31, v155
	v_sub_u32_e32 v182, v182, v165
	v_lshlrev_b32_e32 v182, 11, v182
	v_and_b32_e32 v165, 7, v155
	v_lshrrev_b32_e32 v183, 5, v155
	v_sub_u32_e32 v165, v165, v183
	v_lshl_add_u32 v182, v165, 4, v182
	v_ashrrev_i32_e32 v183, 31, v182
	v_lshrrev_b32_e32 v194, 4, v155
	v_and_b32_e32 v194, 3, v194
	v_and_b32_e32 v165, 7, v155
	v_xor_b32_e32 v194, v194, v165
	v_lshlrev_b32_e32 v194, 4, v194
	v_lshrrev_b32_e32 v165, 3, v155
	v_lshl_add_u32 v194, v165, 7, v194
	v_add_u32_e32 v194, v156, v194
	v_xor_b32_e32 v195, 64, v194
	v_and_b32_e32 v165, 31, v155
	v_lshl_add_u32 v156, v165, 7, v156
	v_lshrrev_b32_e32 v165, 1, v155
	v_and_b32_e32 v165, 7, v165
	v_lshrrev_b32_e32 v155, 5, v155
	v_add_u32_e32 v244, 0, v155
	v_xor_b32_e32 v244, v244, v165
	v_lshl_add_u32 v244, v244, 4, v156
	v_add_u32_e32 v245, 2, v155
	v_xor_b32_e32 v245, v245, v165
	v_lshl_add_u32 v245, v245, 4, v156
	v_add_u32_e32 v246, 4, v155
	v_xor_b32_e32 v246, v246, v165
	v_lshl_add_u32 v246, v246, 4, v156
	v_add_u32_e32 v193, 6, v155
	v_xor_b32_e32 v193, v193, v165
	v_lshl_add_u32 v193, v193, 4, v156
	s_mov_b32 s80, 0x4000
	s_mov_b32 s81, 0
	s_mov_b32 s82, 0xffff4000
	s_mov_b32 s83, -1
	s_and_b32 s76, s2, 0xffffffe0
	s_and_b32 s77, s2, 7
	s_lshl_b32 s77, s77, 2
	s_or_b32 s76, s76, s77
	s_bfe_u32 s77, s2, 0x20003
	s_or_b32 s76, s76, s77
	s_and_b32 s77, s3, 31
	s_cmp_eq_u32 s77, 0
	s_cselect_b32 s76, s76, s2
	v_and_b32_e32 v6, 1, v187
	v_lshlrev_b32_e32 v34, 4, v6
	v_mov_b32_e32 v35, 0
	s_lshr_b32 s8, s4, 6
	s_mov_b32 s5, 0
	v_lshl_add_u64 v[2:3], s[34:35], 0, v[34:35]
	s_lshl_b32 s4, s8, 8
	v_lshl_add_u64 v[36:37], v[2:3], 0, s[4:5]
	v_mbcnt_lo_u32_b32 v2, -1, 0
	v_lshl_add_u64 v[4:5], s[26:27], 0, v[34:35]
	v_mbcnt_hi_u32_b32 v2, -1, v2
	v_and_b32_e32 v42, 31, v1
	v_lshl_add_u64 v[38:39], v[4:5], 0, s[4:5]
	v_and_b32_e32 v4, 64, v2
	v_lshlrev_b32_e32 v6, 10, v6
	v_lshlrev_b32_e32 v7, 2, v42
	v_xor_b32_e32 v3, 8, v2
	v_add_u32_e32 v4, 64, v4
	v_add3_u32 v7, 0, v6, v7
	v_and_b32_e32 v6, 0x3f00, v184
	s_lshl_b32 s4, s8, 13
	v_cmp_lt_i32_e32 vcc, v3, v4
	v_add_u32_e32 v8, 0, v6
	v_and_b32_e32 v9, 0xf0, v184
	v_and_b32_e32 v10, 1, v185
	v_and_b32_e32 v6, 28, v186
	v_cndmask_b32_e32 v2, v2, v3, vcc
	v_add_u32_e32 v45, s4, v7
	s_movk_i32 s26, 0xf000
	v_lshrrev_b32_e32 v1, 4, v1
	v_lshlrev_b32_e32 v43, 7, v10
	v_cmp_eq_u32_e64 s[0:1], 0, v10
	v_lshlrev_b32_e32 v44, 2, v2
	s_lshl_b32 s8, s76, 3
	s_lshl_b32 s9, s3, 3
	s_lshl_b32 s33, s76, 5
	s_lshl_b32 s66, s3, 5
	s_mov_b32 s67, 0x40000
	v_add_u32_e32 v46, v8, v9
	v_mov_b32_e32 v47, 0x358637bd
	s_mov_b32 s68, 0x800000
	s_mov_b32 s27, -1
	v_lshlrev_b32_e32 v40, 1, v6
	v_add_u32_e32 v48, 0x800, v45
	v_add_u32_e32 v49, 0x1000, v45
	v_add_u32_e32 v50, 0x1800, v45
	s_mov_b32 s69, s76
	s_branch .LBB0_339

; #define LAS __attribute__((address_space(3)))
; DI float dot2bf(unsigned a, unsigned b, float c) { return __builtin_amdgcn_fdot2_f32_bf16(__builtin_bit_cast(bf16x2_t, a), __builtin_bit_cast(bf16x2_t, b), c, false); }
; DI void phase_conv(const Params& p, LAS unsigned char* lds) {
;     ...
;             const LAS float* pr = (const LAS float*)(lds + CV_PAR) + c0;
;             f32x4 ac0 = *(const LAS f32x4*)pr, ac1 = *(const LAS f32x4*)(pr + 4);
;             const LAS unsigned char* eb = lds + (r >> 1) * 2048 + lane * 16;
; #pragma unroll
;             for (int q = 0; q < 16; ++q) {
;                 const u32x4 e0 = *(const LAS u32x4*)(eb + q * 2048), e1 = *(const LAS u32x4*)(eb + q * 2048 + 1024);
;                 ac0[0] = dot2bf(e0.x, wp[q][0], ac0[0]); ac0[1] = dot2bf(e0.y, wp[q][1], ac0[1]); ac0[2] = dot2bf(e0.z, wp[q][2], ac0[2]); ac0[3] = dot2bf(e0.w, wp[q][3], ac0[3]);
;                 ac1[0] = dot2bf(e1.x, wp[q][4], ac1[0]); ac1[1] = dot2bf(e1.y, wp[q][5], ac1[1]); ac1[2] = dot2bf(e1.z, wp[q][6], ac1[2]); ac1[3] = dot2bf(e1.w, wp[q][7], ac1[3]);
;                 if ((q & 1) == 1) __builtin_amdgcn_sched_barrier(0);
;             }
.LBB0_425:
	s_and_b32 s1, s90, 0xfffff800
	v_add_u32_e32 v189, s1, v180
	ds_read_b128 v[190:193], v189
	ds_read_b128 v[22:25], v179
	ds_read_b128 v[18:21], v179 offset:16
	ds_read_b128 v[194:197], v189 offset:1024
	s_waitcnt lgkmcnt(2)
	v_dot2c_f32_bf16_e32 v22, v190, v1
	v_dot2c_f32_bf16_e32 v23, v191, v53
	v_dot2c_f32_bf16_e32 v24, v192, v55
	v_dot2c_f32_bf16_e32 v25, v193, v57
	ds_read_b128 v[190:193], v189 offset:3072
	ds_read_b128 v[198:201], v189 offset:2048
	s_waitcnt lgkmcnt(2)
	v_dot2c_f32_bf16_e32 v18, v194, v52
	v_dot2c_f32_bf16_e32 v19, v195, v54
	v_dot2c_f32_bf16_e32 v20, v196, v56
	v_dot2c_f32_bf16_e32 v21, v197, v58
	s_waitcnt lgkmcnt(0)
	v_dot2c_f32_bf16_e32 v22, v198, v59
	v_dot2c_f32_bf16_e32 v23, v199, v61
	v_dot2c_f32_bf16_e32 v24, v200, v63
	v_dot2c_f32_bf16_e32 v25, v201, v65
	v_dot2c_f32_bf16_e32 v18, v190, v60
	v_dot2c_f32_bf16_e32 v19, v191, v62
	v_dot2c_f32_bf16_e32 v20, v192, v64
	v_dot2c_f32_bf16_e32 v21, v193, v66
	ds_read_b128 v[190:193], v189 offset:4096
	ds_read_b128 v[194:197], v189 offset:5120
	s_waitcnt lgkmcnt(1)
	v_dot2c_f32_bf16_e32 v22, v190, v67
	v_dot2c_f32_bf16_e32 v23, v191, v69
	v_dot2c_f32_bf16_e32 v24, v192, v71
	v_dot2c_f32_bf16_e32 v25, v193, v73
	ds_read_b128 v[190:193], v189 offset:7168
	ds_read_b128 v[198:201], v189 offset:6144
	s_waitcnt lgkmcnt(2)
	v_dot2c_f32_bf16_e32 v18, v194, v68
	v_dot2c_f32_bf16_e32 v19, v195, v70
	v_dot2c_f32_bf16_e32 v20, v196, v72
	v_dot2c_f32_bf16_e32 v21, v197, v74
	s_waitcnt lgkmcnt(0)
	v_dot2c_f32_bf16_e32 v22, v198, v75
	v_dot2c_f32_bf16_e32 v23, v199, v77
	v_dot2c_f32_bf16_e32 v24, v200, v79
	v_dot2c_f32_bf16_e32 v25, v201, v81
	v_dot2c_f32_bf16_e32 v18, v190, v76
	v_dot2c_f32_bf16_e32 v19, v191, v78
	v_dot2c_f32_bf16_e32 v20, v192, v80
	v_dot2c_f32_bf16_e32 v21, v193, v82
	ds_read_b128 v[190:193], v189 offset:8192
	ds_read_b128 v[194:197], v189 offset:9216
	s_waitcnt lgkmcnt(1)
	v_dot2c_f32_bf16_e32 v22, v190, v83
	v_dot2c_f32_bf16_e32 v23, v191, v85
	v_dot2c_f32_bf16_e32 v24, v192, v87
	v_dot2c_f32_bf16_e32 v25, v193, v89
	ds_read_b128 v[190:193], v189 offset:11264
	ds_read_b128 v[198:201], v189 offset:10240
	s_waitcnt lgkmcnt(2)
	v_dot2c_f32_bf16_e32 v18, v194, v84
	v_dot2c_f32_bf16_e32 v19, v195, v86
	v_dot2c_f32_bf16_e32 v20, v196, v88
	v_dot2c_f32_bf16_e32 v21, v197, v90
	s_waitcnt lgkmcnt(0)
	v_dot2c_f32_bf16_e32 v22, v198, v91
	v_dot2c_f32_bf16_e32 v23, v199, v93
	v_dot2c_f32_bf16_e32 v24, v200, v95
	v_dot2c_f32_bf16_e32 v25, v201, v97
	v_dot2c_f32_bf16_e32 v18, v190, v92
	v_dot2c_f32_bf16_e32 v19, v191, v94
	v_dot2c_f32_bf16_e32 v20, v192, v96
	v_dot2c_f32_bf16_e32 v21, v193, v98
	ds_read_b128 v[190:193], v189 offset:12288
	ds_read_b128 v[194:197], v189 offset:13312
	s_waitcnt lgkmcnt(1)
	v_dot2c_f32_bf16_e32 v22, v190, v99
	v_dot2c_f32_bf16_e32 v23, v191, v101
	v_dot2c_f32_bf16_e32 v24, v192, v103
	v_dot2c_f32_bf16_e32 v25, v193, v105
	ds_read_b128 v[190:193], v189 offset:15360
	ds_read_b128 v[198:201], v189 offset:14336
	s_waitcnt lgkmcnt(2)
	v_dot2c_f32_bf16_e32 v18, v194, v100
	v_dot2c_f32_bf16_e32 v19, v195, v102
	v_dot2c_f32_bf16_e32 v20, v196, v104
	v_dot2c_f32_bf16_e32 v21, v197, v106
	s_waitcnt lgkmcnt(0)
	v_dot2c_f32_bf16_e32 v22, v198, v107
	v_dot2c_f32_bf16_e32 v23, v199, v109
	v_dot2c_f32_bf16_e32 v24, v200, v111
	v_dot2c_f32_bf16_e32 v25, v201, v113
	v_dot2c_f32_bf16_e32 v18, v190, v108
	v_dot2c_f32_bf16_e32 v19, v191, v110
	v_dot2c_f32_bf16_e32 v20, v192, v112
	v_dot2c_f32_bf16_e32 v21, v193, v114
	ds_read_b128 v[190:193], v189 offset:16384
	ds_read_b128 v[194:197], v189 offset:17408
	s_waitcnt lgkmcnt(1)
	v_dot2c_f32_bf16_e32 v22, v190, v115
	v_dot2c_f32_bf16_e32 v23, v191, v117
	v_dot2c_f32_bf16_e32 v24, v192, v119
	v_dot2c_f32_bf16_e32 v25, v193, v121
	ds_read_b128 v[190:193], v189 offset:19456
	ds_read_b128 v[198:201], v189 offset:18432
	s_waitcnt lgkmcnt(2)
	v_dot2c_f32_bf16_e32 v18, v194, v116
	v_dot2c_f32_bf16_e32 v19, v195, v118
	v_dot2c_f32_bf16_e32 v20, v196, v120
	v_dot2c_f32_bf16_e32 v21, v197, v122
	s_waitcnt lgkmcnt(0)
	v_dot2c_f32_bf16_e32 v22, v198, v123
	v_dot2c_f32_bf16_e32 v23, v199, v125
	v_dot2c_f32_bf16_e32 v24, v200, v127
	v_dot2c_f32_bf16_e32 v25, v201, v129
	v_dot2c_f32_bf16_e32 v18, v190, v124
	v_dot2c_f32_bf16_e32 v19, v191, v126
	v_dot2c_f32_bf16_e32 v20, v192, v128
	v_dot2c_f32_bf16_e32 v21, v193, v130
	ds_read_b128 v[190:193], v189 offset:20480
	ds_read_b128 v[194:197], v189 offset:21504
	s_waitcnt lgkmcnt(1)
	v_dot2c_f32_bf16_e32 v22, v190, v131
	v_dot2c_f32_bf16_e32 v23, v191, v133
	v_dot2c_f32_bf16_e32 v24, v192, v135
	v_dot2c_f32_bf16_e32 v25, v193, v137
	ds_read_b128 v[190:193], v189 offset:23552
	ds_read_b128 v[198:201], v189 offset:22528
	s_waitcnt lgkmcnt(2)
	v_dot2c_f32_bf16_e32 v18, v194, v132
	v_dot2c_f32_bf16_e32 v19, v195, v134
	v_dot2c_f32_bf16_e32 v20, v196, v136
	v_dot2c_f32_bf16_e32 v21, v197, v138
	s_waitcnt lgkmcnt(0)
	v_dot2c_f32_bf16_e32 v22, v198, v139
	v_dot2c_f32_bf16_e32 v23, v199, v141
	v_dot2c_f32_bf16_e32 v24, v200, v143
	v_dot2c_f32_bf16_e32 v25, v201, v145
	v_dot2c_f32_bf16_e32 v18, v190, v140
	v_dot2c_f32_bf16_e32 v19, v191, v142
	v_dot2c_f32_bf16_e32 v20, v192, v144
	v_dot2c_f32_bf16_e32 v21, v193, v146
	ds_read_b128 v[190:193], v189 offset:24576
	ds_read_b128 v[194:197], v189 offset:25600
	s_waitcnt lgkmcnt(1)
	v_dot2c_f32_bf16_e32 v22, v190, v147
	v_dot2c_f32_bf16_e32 v23, v191, v149
	v_dot2c_f32_bf16_e32 v24, v192, v151
	v_dot2c_f32_bf16_e32 v25, v193, v153
	ds_read_b128 v[190:193], v189 offset:27648
	ds_read_b128 v[198:201], v189 offset:26624
	s_waitcnt lgkmcnt(2)
	v_dot2c_f32_bf16_e32 v18, v194, v148
	v_dot2c_f32_bf16_e32 v19, v195, v150
	v_dot2c_f32_bf16_e32 v20, v196, v152
	v_dot2c_f32_bf16_e32 v21, v197, v154
	s_waitcnt lgkmcnt(0)
; #define LAS __attribute__((address_space(3)))
; DI float dot2bf(unsigned a, unsigned b, float c) { return __builtin_amdgcn_fdot2_f32_bf16(__builtin_bit_cast(bf16x2_t, a), __builtin_bit_cast(bf16x2_t, b), c, false); }
; DI float wave_sum(float v) {
; #pragma unroll
;     for (int o = 1; o < 64; o <<= 1) v += __shfl_xor(v, o);
;     return v;
; DI void phase_conv(const Params& p, LAS unsigned char* lds) {
;     ...
;             for (int q = 0; q < 16; ++q) {
;                 const u32x4 e0 = *(const LAS u32x4*)(eb + q * 2048), e1 = *(const LAS u32x4*)(eb + q * 2048 + 1024);
;                 ac0[0] = dot2bf(e0.x, wp[q][0], ac0[0]); ac0[1] = dot2bf(e0.y, wp[q][1], ac0[1]); ac0[2] = dot2bf(e0.z, wp[q][2], ac0[2]); ac0[3] = dot2bf(e0.w, wp[q][3], ac0[3]);
;                 ac1[0] = dot2bf(e1.x, wp[q][4], ac1[0]); ac1[1] = dot2bf(e1.y, wp[q][5], ac1[1]); ac1[2] = dot2bf(e1.z, wp[q][6], ac1[2]); ac1[3] = dot2bf(e1.w, wp[q][7], ac1[3]);
;                 if ((q & 1) == 1) __builtin_amdgcn_sched_barrier(0);
;             }
;             const float mean = wave_sum((ac0[0] + ac0[1]) + (ac0[2] + ac0[3]) + (ac1[0] + ac1[1]) + (ac1[2] + ac1[3])) * (1.0f / 512.0f);
;             ac0 -= mean; ac1 -= mean;
;             const float rstd = rsqrtf(wave_sum((ac0[0] * ac0[0] + ac0[1] * ac0[1]) + (ac0[2] * ac0[2] + ac0[3] * ac0[3]) + (ac1[0] * ac1[0] + ac1[1] * ac1[1]) + (ac1[2] * ac1[2] + ac1[3] * ac1[3])) * (1.0f / 512.0f) + 1e-5f);
	v_dot2c_f32_bf16_e32 v22, v198, v155
	v_dot2c_f32_bf16_e32 v23, v199, v157
	v_dot2c_f32_bf16_e32 v24, v200, v159
	v_dot2c_f32_bf16_e32 v25, v201, v161
	v_dot2c_f32_bf16_e32 v18, v190, v156
	v_dot2c_f32_bf16_e32 v19, v191, v158
	v_dot2c_f32_bf16_e32 v20, v192, v160
	v_dot2c_f32_bf16_e32 v21, v193, v162
	ds_read_b128 v[190:193], v189 offset:28672
	ds_read_b128 v[194:197], v189 offset:29696
	s_waitcnt lgkmcnt(1)
	v_dot2c_f32_bf16_e32 v22, v190, v163
	v_dot2c_f32_bf16_e32 v23, v191, v165
	v_dot2c_f32_bf16_e32 v24, v192, v167
	v_dot2c_f32_bf16_e32 v25, v193, v169
	ds_read_b128 v[190:193], v189 offset:31744
	ds_read_b128 v[198:201], v189 offset:30720
	s_waitcnt lgkmcnt(2)
	v_dot2c_f32_bf16_e32 v18, v194, v164
	v_dot2c_f32_bf16_e32 v19, v195, v166
	v_dot2c_f32_bf16_e32 v20, v196, v168
	v_dot2c_f32_bf16_e32 v21, v197, v170
	s_waitcnt lgkmcnt(0)
	v_dot2c_f32_bf16_e32 v22, v198, v171
	v_dot2c_f32_bf16_e32 v23, v199, v173
	v_dot2c_f32_bf16_e32 v24, v200, v175
	v_dot2c_f32_bf16_e32 v25, v201, v177
	v_dot2c_f32_bf16_e32 v18, v190, v172
	v_dot2c_f32_bf16_e32 v19, v191, v174
	v_dot2c_f32_bf16_e32 v20, v192, v176
	v_dot2c_f32_bf16_e32 v21, v193, v178
	v_mov_b32_e32 v190, v22
	v_mov_b32_e32 v191, v24
	v_mov_b32_e32 v192, v23
	v_mov_b32_e32 v193, v25
	v_pk_add_f32 v[190:191], v[190:191], v[192:193]
	v_add_f32_e32 v193, v18, v19
	v_pk_add_f32 v[190:191], v[190:191], v[190:191] op_sel_hi:[0,1]
	v_mov_b32_e32 v192, v20
	v_mov_b32_e32 v190, v21
	v_pk_add_f32 v[190:191], v[192:193], v[190:191]
	s_lshl_b64 s[72:73], s[72:73], 11
	v_add_f32_e32 v189, v190, v191
	s_waitcnt vmcnt(0)
	v_lshlrev_b32_e32 v210, 16, v10
	v_and_b32_e32 v211, 0xffff0000, v10
	v_lshlrev_b32_e32 v10, 16, v11
	v_and_b32_e32 v11, 0xffff0000, v11
	s_waitcnt lgkmcnt(0)
	s_nop 1
	v_add_f32_dpp v189, v189, v189 quad_perm:[1,0,3,2] row_mask:0xf bank_mask:0xf
	v_lshlrev_b32_e32 v212, 16, v14
	v_and_b32_e32 v213, 0xffff0000, v14
	v_lshlrev_b32_e32 v14, 16, v15
	v_and_b32_e32 v15, 0xffff0000, v15
	s_waitcnt lgkmcnt(0)
	s_nop 1
	v_add_f32_dpp v189, v189, v189 quad_perm:[2,3,0,1] row_mask:0xf bank_mask:0xf
	v_lshlrev_b32_e32 v208, 16, v6
	v_and_b32_e32 v209, 0xffff0000, v6
	v_lshlrev_b32_e32 v6, 16, v7
	v_and_b32_e32 v7, 0xffff0000, v7
	s_waitcnt lgkmcnt(0)
	s_nop 1
	v_add_f32_dpp v189, v189, v189 row_half_mirror row_mask:0xf bank_mask:0xf
	v_lshlrev_b32_e32 v214, 16, v2
	v_and_b32_e32 v215, 0xffff0000, v2
	v_lshlrev_b32_e32 v2, 16, v3
	v_and_b32_e32 v3, 0xffff0000, v3
	s_waitcnt lgkmcnt(0)
	s_nop 1
	v_add_f32_dpp v189, v189, v189 row_mirror row_mask:0xf bank_mask:0xf
	s_add_i32 s89, s89, -1
	s_addk_i32 s90, 0x2000
	s_add_i32 s0, s0, 8
	s_cmp_eq_u32 s89, 0
	s_waitcnt lgkmcnt(0)
	v_mov_b32_e32 v190, v189
	s_nop 1
	v_permlane16_swap_b32_e32 v189, v190
	v_add_f32_e32 v189, v189, v190
	s_waitcnt lgkmcnt(0)
	v_mov_b32_e32 v190, v189
	s_nop 1
	v_permlane32_swap_b32_e32 v189, v190
	v_add_f32_e32 v189, v189, v190
	v_fmac_f32_e32 v23, 0xbb000000, v189
	v_fmac_f32_e32 v22, 0xbb000000, v189
	v_fmac_f32_e32 v25, 0xbb000000, v189
	v_fmac_f32_e32 v24, 0xbb000000, v189
	v_fmac_f32_e32 v19, 0xbb000000, v189
	v_fmac_f32_e32 v18, 0xbb000000, v189
	v_fmac_f32_e32 v21, 0xbb000000, v189
	v_fmac_f32_e32 v20, 0xbb000000, v189
	v_pk_mul_f32 v[190:191], v[24:25], v[24:25]
	v_pk_mul_f32 v[192:193], v[22:23], v[22:23]
	v_pk_mul_f32 v[194:195], v[20:21], v[20:21]
	v_pk_mul_f32 v[196:197], v[18:19], v[18:19]
	v_pk_mov_b32 v[198:199], v[192:193], v[190:191] op_sel:[1,0]
	v_mov_b32_e32 v193, v191
	v_mov_b32_e32 v190, v194
	v_mov_b32_e32 v191, v196
	v_mov_b32_e32 v196, v195
	v_pk_add_f32 v[192:193], v[198:199], v[192:193]
	v_pk_add_f32 v[190:191], v[190:191], v[196:197]
	v_add_f32_e32 v189, v192, v193
	v_add_f32_e32 v189, v191, v189
	v_add_f32_e32 v189, v190, v189
	s_waitcnt lgkmcnt(0)
	s_nop 1
	v_add_f32_dpp v189, v189, v189 quad_perm:[1,0,3,2] row_mask:0xf bank_mask:0xf
	s_waitcnt lgkmcnt(0)
	s_nop 1
	v_add_f32_dpp v189, v189, v189 quad_perm:[2,3,0,1] row_mask:0xf bank_mask:0xf
	s_waitcnt lgkmcnt(0)
	s_nop 1
	v_add_f32_dpp v189, v189, v189 row_half_mirror row_mask:0xf bank_mask:0xf
	s_waitcnt lgkmcnt(0)
	s_nop 1
	v_add_f32_dpp v189, v189, v189 row_mirror row_mask:0xf bank_mask:0xf
	s_waitcnt lgkmcnt(0)
	v_mov_b32_e32 v190, v189
	s_nop 1
	v_permlane16_swap_b32_e32 v189, v190
	v_add_f32_e32 v189, v189, v190
	s_waitcnt lgkmcnt(0)
; #define LAS __attribute__((address_space(3)))
; DI u32x4 pk8(f32x4 a, f32x4 b) { u32x4 w; w.x = pk2(a[0], a[1]); w.y = pk2(a[2], a[3]); w.z = pk2(b[0], b[1]); w.w = pk2(b[2], b[3]); return w; }
; DI void unpack8(const u32x4 w, float (&f)[8]) { f[0] = bflo(w.x); f[1] = bfhi(w.x); f[2] = bflo(w.y); f[3] = bfhi(w.y); f[4] = bflo(w.z); f[5] = bfhi(w.z); f[6] = bflo(w.w); f[7] = bfhi(w.w); }
; DI float sigmoidf_(float x) { return __builtin_amdgcn_rcpf(1.0f + __expf(-x)); }
; DI void phase_conv(const Params& p, LAS unsigned char* lds) {
;     ...
;             const float rstd = rsqrtf(wave_sum((ac0[0] * ac0[0] + ac0[1] * ac0[1]) + (ac0[2] * ac0[2] + ac0[3] * ac0[3]) + (ac1[0] * ac1[0] + ac1[1] * ac1[1]) + (ac1[2] * ac1[2] + ac1[3] * ac1[3])) * (1.0f / 512.0f) + 1e-5f);
;             const f32x4 g0 = *(const LAS f32x4*)(pr + 512), g1 = *(const LAS f32x4*)(pr + 516), b0 = *(const LAS f32x4*)(pr + 1024), b1 = *(const LAS f32x4*)(pr + 1028);
;             f32x4 y0 = ac0 * rstd * g0 + b0, y1 = ac1 * rstd * g1 + b1;
; #pragma unroll
;             for (int k = 0; k < 4; ++k) { y0[k] *= sigmoidf_(y0[k]); y1[k] *= sigmoidf_(y1[k]); }
;             *(u32x4*)(CAT + row * D + c0) = pk8(y0, y1);
;             float fz[8], f1[8], f2[8], fg[8];
;             unpack8(zz, fz); unpack8(z1, f1); unpack8(z2, f2); unpack8(gbv, fg);
;             const f32x4 w00 = *(const LAS f32x4*)(pr + 1536), w01 = *(const LAS f32x4*)(pr + 1540), w10 = *(const LAS f32x4*)(pr + 2048), w11 = *(const LAS f32x4*)(pr + 2052), w20 = *(const LAS f32x4*)(pr + 2560), w21 = *(const LAS f32x4*)(pr + 2564);
;             f32x4 o0, o1;
; #pragma unroll
;             for (int k = 0; k < 4; ++k) { o0[k] = fg[k] * (w00[k] * f2[k] + w10[k] * f1[k] + w20[k] * fz[k]); o1[k] = fg[4 + k] * (w01[k] * f2[4 + k] + w11[k] * f1[4 + k] + w21[k] * fz[4 + k]); }
;             *(u32x4*)(CAT + row * D + MW + c0) = pk8(o0, o1);
	v_mov_b32_e32 v190, v189
	s_nop 1
	v_permlane32_swap_b32_e32 v189, v190
	v_add_f32_e32 v189, v189, v190
	v_fmamk_f32 v189, v189, 0x3b000000, v188
	v_mul_f32_e32 v190, 0x4b800000, v189
	v_cmp_gt_f32_e32 vcc, s87, v189
	s_nop 1
	v_cndmask_b32_e32 v189, v189, v190, vcc
	v_rsq_f32_e32 v189, v189
	ds_read_b128 v[190:193], v179 offset:2048
	ds_read_b128 v[194:197], v179 offset:2064
	ds_read_b128 v[198:201], v179 offset:4096
	ds_read_b128 v[202:205], v179 offset:4112
	v_mul_f32_e32 v206, 0x45800000, v189
	v_cndmask_b32_e32 v206, v189, v206, vcc
	v_pk_mul_f32 v[22:23], v[22:23], v[206:207] op_sel_hi:[1,0]
	v_pk_mul_f32 v[24:25], v[24:25], v[206:207] op_sel_hi:[1,0]
	v_pk_mul_f32 v[18:19], v[18:19], v[206:207] op_sel_hi:[1,0]
	s_waitcnt lgkmcnt(1)
	v_pk_fma_f32 v[22:23], v[190:191], v[22:23], v[198:199]
	v_pk_mul_f32 v[20:21], v[20:21], v[206:207] op_sel_hi:[1,0]
	v_pk_fma_f32 v[24:25], v[192:193], v[24:25], v[200:201]
	s_waitcnt lgkmcnt(0)
	v_pk_fma_f32 v[18:19], v[194:195], v[18:19], v[202:203]
	v_mul_f32_e32 v189, 0xbfb8aa3b, v22
	v_pk_fma_f32 v[20:21], v[196:197], v[20:21], v[204:205]
	v_mul_f32_e32 v190, 0xbfb8aa3b, v18
	v_mul_f32_e32 v195, 0xbfb8aa3b, v25
	v_exp_f32_e32 v189, v189
	v_mul_f32_e32 v191, 0xbfb8aa3b, v23
	v_mul_f32_e32 v192, 0xbfb8aa3b, v19
	v_mul_f32_e32 v193, 0xbfb8aa3b, v24
	v_mul_f32_e32 v194, 0xbfb8aa3b, v20
	v_mul_f32_e32 v196, 0xbfb8aa3b, v21
	v_exp_f32_e32 v190, v190
	v_exp_f32_e32 v195, v195
	v_exp_f32_e32 v191, v191
	v_exp_f32_e32 v192, v192
	v_exp_f32_e32 v193, v193
	v_exp_f32_e32 v194, v194
	v_exp_f32_e32 v197, v196
	v_add_f32_e32 v189, 1.0, v189
	v_add_f32_e32 v196, 1.0, v190
	v_rcp_f32_e32 v190, v189
	v_add_f32_e32 v189, 1.0, v195
	v_add_f32_e32 v191, 1.0, v191
	v_add_f32_e32 v198, 1.0, v192
	v_add_f32_e32 v199, 1.0, v193
	v_add_f32_e32 v200, 1.0, v194
	v_rcp_f32_e32 v195, v189
	v_add_f32_e32 v189, 1.0, v197
	v_rcp_f32_e32 v192, v196
	v_rcp_f32_e32 v191, v191
	v_rcp_f32_e32 v193, v198
	v_rcp_f32_e32 v194, v199
	v_rcp_f32_e32 v196, v200
	v_rcp_f32_e32 v197, v189
	v_pk_mul_f32 v[22:23], v[22:23], v[190:191]
	v_pk_mul_f32 v[190:191], v[18:19], v[192:193]
	v_pk_mul_f32 v[24:25], v[24:25], v[194:195]
	v_pk_mul_f32 v[192:193], v[20:21], v[196:197]
	v_cvt_pk_bf16_f32 v18, v22, v23
	v_cvt_pk_bf16_f32 v19, v24, v25
	v_cvt_pk_bf16_f32 v20, v190, v191
	v_cvt_pk_bf16_f32 v21, v192, v193
	v_lshl_add_u64 v[206:207], v[40:41], 0, s[72:73]
	global_store_dwordx4 v[206:207], v[18:21], off
	ds_read_b128 v[18:21], v179 offset:6144
	ds_read_b128 v[22:25], v179 offset:6160
	ds_read_b128 v[190:193], v179 offset:8192
	ds_read_b128 v[194:197], v179 offset:8208
	ds_read_b128 v[198:201], v179 offset:10240
	ds_read_b128 v[202:205], v179 offset:10256
	s_waitcnt lgkmcnt(3)
	v_pk_mul_f32 v[10:11], v[192:193], v[10:11]
	v_pk_mul_f32 v[190:191], v[190:191], v[210:211]
	v_pk_fma_f32 v[10:11], v[20:21], v[14:15], v[10:11]
	v_pk_fma_f32 v[18:19], v[18:19], v[212:213], v[190:191]
	s_waitcnt lgkmcnt(1)
	v_pk_fma_f32 v[6:7], v[200:201], v[6:7], v[10:11]
	v_pk_fma_f32 v[18:19], v[198:199], v[208:209], v[18:19]
	v_lshlrev_b32_e32 v190, 16, v8
	v_and_b32_e32 v191, 0xffff0000, v8
	v_lshlrev_b32_e32 v198, 16, v12
	v_and_b32_e32 v199, 0xffff0000, v12
	v_pk_mul_f32 v[6:7], v[6:7], v[2:3]
	v_lshlrev_b32_e32 v2, 16, v9
	v_and_b32_e32 v3, 0xffff0000, v9
	v_lshlrev_b32_e32 v8, 16, v13
	v_and_b32_e32 v9, 0xffff0000, v13
	v_lshlrev_b32_e32 v208, 16, v16
	v_and_b32_e32 v209, 0xffff0000, v16
	v_pk_mul_f32 v[194:195], v[194:195], v[198:199]
	v_lshlrev_b32_e32 v10, 16, v17
	v_and_b32_e32 v11, 0xffff0000, v17
	v_pk_mul_f32 v[8:9], v[196:197], v[8:9]
	v_pk_fma_f32 v[22:23], v[22:23], v[208:209], v[194:195]
	v_pk_fma_f32 v[8:9], v[24:25], v[10:11], v[8:9]
	v_lshlrev_b32_e32 v210, 16, v4
	v_and_b32_e32 v211, 0xffff0000, v4
	s_waitcnt lgkmcnt(0)
	v_pk_fma_f32 v[22:23], v[202:203], v[190:191], v[22:23]
	v_lshlrev_b32_e32 v4, 16, v5
	v_and_b32_e32 v5, 0xffff0000, v5
	v_pk_fma_f32 v[2:3], v[204:205], v[2:3], v[8:9]
	v_pk_mul_f32 v[18:19], v[18:19], v[214:215]
	v_pk_mul_f32 v[22:23], v[22:23], v[210:211]
	v_pk_mul_f32 v[8:9], v[2:3], v[4:5]
	v_cvt_pk_bf16_f32 v2, v18, v19
	v_cvt_pk_bf16_f32 v3, v6, v7
	v_cvt_pk_bf16_f32 v4, v22, v23
	v_cvt_pk_bf16_f32 v5, v8, v9
	global_store_dwordx4 v[206:207], v[2:5], off offset:1024
	s_cbranch_scc1 .LBB0_437

; template <class EpiS>
; DI void sample_gemm(LAS unsigned char* lds, const bf16_t* A, const bf16_t* Bt, int nN, int K, const EpiS& E) {
;     const int tid = threadIdx.x, lane = tid & 63, w = __builtin_amdgcn_readfirstlane(tid >> 6), r32 = lane & 31, h = lane >> 5;
;     const int nunits = 16 * nN, kw = K >> 3, nk = kw >> 4;
;     for (int un = (int)blockIdx.x; un < nunits; un += (int)gridDim.x) {
;         const int rb = un & 3, wc = (un >> 2) & 3, pn = un >> 4;
;         const bf16_t* ap = A + (size_t)(MP + rb * 32 + r32) * K + w * kw + h * 8;
;         const bf16_t* b0p = Bt + (size_t)(pn * 256 + wc * 32 + r32) * K + w * kw + h * 8;
;         const bf16_t* b1p = b0p + (size_t)128 * K;
.LBB0_543:
	s_cmp_gt_i32 s2, 63
	v_readfirstlane_b32 s0, v206
	s_cbranch_scc1 .LBB0_548
	v_and_b32_e32 v155, 63, v206
	v_lshrrev_b32_e32 v156, 6, v206
	v_and_b32_e32 v156, 7, v156
	v_lshlrev_b32_e32 v156, 13, v156
	v_add_u32_e32 v156, 0x10000, v156
	v_lshrrev_b32_e32 v182, 3, v155
	v_and_b32_e32 v165, 31, v155
	v_sub_u32_e32 v182, v182, v165
	v_lshlrev_b32_e32 v182, 11, v182
	v_and_b32_e32 v165, 7, v155
	v_lshrrev_b32_e32 v183, 5, v155
	v_sub_u32_e32 v165, v165, v183
	v_lshl_add_u32 v182, v165, 4, v182
	v_ashrrev_i32_e32 v183, 31, v182
	v_lshrrev_b32_e32 v194, 4, v155
	v_and_b32_e32 v194, 3, v194
	v_and_b32_e32 v165, 7, v155
	v_xor_b32_e32 v194, v194, v165
	v_lshlrev_b32_e32 v194, 4, v194
	v_lshrrev_b32_e32 v165, 3, v155
	v_lshl_add_u32 v194, v165, 7, v194
	v_add_u32_e32 v194, v156, v194
	v_xor_b32_e32 v195, 64, v194
	v_and_b32_e32 v165, 31, v155
	v_lshl_add_u32 v156, v165, 7, v156
	v_lshrrev_b32_e32 v165, 1, v155
	v_and_b32_e32 v165, 7, v165
	v_lshrrev_b32_e32 v155, 5, v155
	v_add_u32_e32 v244, 0, v155
	v_xor_b32_e32 v244, v244, v165
	v_lshl_add_u32 v244, v244, 4, v156
	v_add_u32_e32 v245, 2, v155
	v_xor_b32_e32 v245, v245, v165
	v_lshl_add_u32 v245, v245, 4, v156
	v_add_u32_e32 v246, 4, v155
	v_xor_b32_e32 v246, v246, v165
	v_lshl_add_u32 v246, v246, 4, v156
	v_add_u32_e32 v193, 6, v155
	v_xor_b32_e32 v193, v193, v165
	v_lshl_add_u32 v193, v193, 4, v156
	s_mov_b32 s80, 0x4000
	s_mov_b32 s81, 0
	s_mov_b32 s82, 0xffff4000
	s_mov_b32 s83, -1
	s_and_b32 s76, s2, 0xffffffe0
	s_and_b32 s77, s2, 7
	s_lshl_b32 s77, s77, 2
	s_or_b32 s76, s76, s77
	s_bfe_u32 s77, s2, 0x20003
	s_or_b32 s76, s76, s77
	s_and_b32 s77, s3, 31
	s_cmp_eq_u32 s77, 0
	s_cselect_b32 s76, s76, s2
	v_and_b32_e32 v6, 1, v210
	v_lshlrev_b32_e32 v34, 4, v6
	v_mov_b32_e32 v35, 0
	s_add_u32 s4, s14, 0xf8000000
	v_lshl_add_u64 v[4:5], s[10:11], 0, v[34:35]
	v_and_b32_e32 v9, 28, v209
	s_movk_i32 s10, 0x80
	s_addc_u32 s5, s15, -1
	v_and_or_b32 v41, v207, s10, v9
	s_lshr_b32 s10, s0, 6
	s_mov_b32 s1, 0
	s_waitcnt lgkmcnt(0)
	v_lshl_add_u64 v[2:3], s[26:27], 0, v[34:35]
	s_lshl_b32 s0, s10, 8
	v_lshl_add_u64 v[36:37], v[2:3], 0, s[0:1]
	v_mbcnt_lo_u32_b32 v2, -1, 0
	v_mbcnt_hi_u32_b32 v2, -1, v2
	v_lshl_add_u64 v[38:39], v[4:5], 0, s[0:1]
	v_and_b32_e32 v4, 64, v2
	v_xor_b32_e32 v3, 1, v2
	v_add_u32_e32 v4, 64, v4
	v_cmp_lt_i32_e64 s[0:1], v3, v4
	v_and_b32_e32 v40, 31, v206
	v_lshlrev_b32_e32 v6, 10, v6
	v_cndmask_b32_e64 v3, v2, v3, s[0:1]
	v_lshlrev_b32_e32 v42, 2, v3
	v_xor_b32_e32 v3, 2, v2
	v_cmp_lt_i32_e64 s[0:1], v3, v4
	v_lshlrev_b32_e32 v7, 2, v40
	v_add3_u32 v6, 0, v6, v7
	v_cndmask_b32_e64 v3, v2, v3, s[0:1]
	v_lshlrev_b32_e32 v43, 2, v3
	v_xor_b32_e32 v3, 4, v2
	v_cmp_lt_i32_e64 s[0:1], v3, v4
	v_and_b32_e32 v7, 0x3f00, v207
	s_lshl_b32 s17, s10, 13
	v_cndmask_b32_e64 v3, v2, v3, s[0:1]
	v_lshlrev_b32_e32 v44, 2, v3
	v_xor_b32_e32 v3, 8, v2
	v_cmp_lt_i32_e64 s[0:1], v3, v4
	v_add_u32_e32 v7, 0, v7
	v_and_b32_e32 v8, 0xf0, v207
	v_cndmask_b32_e64 v2, v2, v3, s[0:1]
	v_add_u32_e32 v46, s17, v6
	v_cmp_eq_u32_e32 vcc, 0, v208
	v_lshlrev_b32_e32 v45, 2, v2
	s_lshl_b32 s10, s76, 3
	s_lshl_b32 s11, s3, 3
	s_lshl_b32 s12, s76, 4
	s_lshl_b32 s13, s3, 4
	s_lshl_b32 s14, s76, 5
	s_lshl_b32 s15, s3, 5
	s_mov_b32 s16, 0x40000
	v_add_u32_e32 v47, v7, v8
	v_add_u32_e32 v48, 0x800, v46
	v_add_u32_e32 v49, 0x1000, v46
	v_add_u32_e32 v50, 0x1800, v46
	s_mov_b32 s17, s76
	s_branch .LBB0_546

; template <class EpiS>
; DI void sample_gemm(LAS unsigned char* lds, const bf16_t* A, const bf16_t* Bt, int nN, int K, const EpiS& E) {
;     const int tid = threadIdx.x, lane = tid & 63, w = __builtin_amdgcn_readfirstlane(tid >> 6), r32 = lane & 31, h = lane >> 5;
;     const int nunits = 16 * nN, kw = K >> 3, nk = kw >> 4;
;     for (int un = (int)blockIdx.x; un < nunits; un += (int)gridDim.x) {
;         const int rb = un & 3, wc = (un >> 2) & 3, pn = un >> 4;
;         const bf16_t* ap = A + (size_t)(MP + rb * 32 + r32) * K + w * kw + h * 8;
;         const bf16_t* b0p = Bt + (size_t)(pn * 256 + wc * 32 + r32) * K + w * kw + h * 8;
;         const bf16_t* b1p = b0p + (size_t)128 * K;
.LBB0_616:
	s_cmpk_gt_i32 s2, 0x15f
	v_readfirstlane_b32 s0, v162
	s_cbranch_scc1 .LBB0_621
	v_and_b32_e32 v155, 63, v162
	v_lshrrev_b32_e32 v156, 6, v162
	v_and_b32_e32 v156, 7, v156
	v_lshlrev_b32_e32 v156, 13, v156
	v_add_u32_e32 v156, 0x10000, v156
	v_lshrrev_b32_e32 v182, 3, v155
	v_and_b32_e32 v165, 31, v155
	v_sub_u32_e32 v182, v182, v165
	v_lshlrev_b32_e32 v182, 11, v182
	v_and_b32_e32 v165, 7, v155
	v_lshrrev_b32_e32 v183, 5, v155
	v_sub_u32_e32 v165, v165, v183
	v_lshl_add_u32 v182, v165, 4, v182
	v_ashrrev_i32_e32 v183, 31, v182
	v_lshrrev_b32_e32 v194, 4, v155
	v_and_b32_e32 v194, 3, v194
	v_and_b32_e32 v165, 7, v155
	v_xor_b32_e32 v194, v194, v165
	v_lshlrev_b32_e32 v194, 4, v194
	v_lshrrev_b32_e32 v165, 3, v155
	v_lshl_add_u32 v194, v165, 7, v194
	v_add_u32_e32 v194, v156, v194
	v_xor_b32_e32 v195, 64, v194
	v_and_b32_e32 v165, 31, v155
	v_lshl_add_u32 v156, v165, 7, v156
	v_lshrrev_b32_e32 v165, 1, v155
	v_and_b32_e32 v165, 7, v165
	v_lshrrev_b32_e32 v155, 5, v155
	v_add_u32_e32 v244, 0, v155
	v_xor_b32_e32 v244, v244, v165
	v_lshl_add_u32 v244, v244, 4, v156
	v_add_u32_e32 v245, 2, v155
	v_xor_b32_e32 v245, v245, v165
	v_lshl_add_u32 v245, v245, 4, v156
	v_add_u32_e32 v246, 4, v155
	v_xor_b32_e32 v246, v246, v165
	v_lshl_add_u32 v246, v246, 4, v156
	v_add_u32_e32 v193, 6, v155
	v_xor_b32_e32 v193, v193, v165
	v_lshl_add_u32 v193, v193, 4, v156
	s_mov_b32 s80, 0x4000
	s_mov_b32 s81, 0
	s_mov_b32 s82, 0xffff4000
	s_mov_b32 s83, -1
	s_and_b32 s76, s2, 0xffffffe0
	s_and_b32 s77, s2, 7
	s_lshl_b32 s77, s77, 2
	s_or_b32 s76, s76, s77
	s_bfe_u32 s77, s2, 0x20003
	s_or_b32 s76, s76, s77
	s_and_b32 s77, s3, 31
	s_cmp_eq_u32 s77, 0
	s_cselect_b32 s76, s76, s2
	v_and_b32_e32 v6, 1, v1
	v_lshlrev_b32_e32 v34, 4, v6
	v_mov_b32_e32 v35, 0
	s_lshr_b32 s0, s0, 6
	s_mov_b32 s5, 0
	v_lshl_add_u64 v[2:3], s[34:35], 0, v[34:35]
	s_lshl_b32 s4, s0, 8
	v_lshl_add_u64 v[36:37], v[2:3], 0, s[4:5]
	v_mbcnt_lo_u32_b32 v2, -1, 0
	v_and_b32_e32 v42, 31, v162
	v_lshl_add_u64 v[4:5], s[52:53], 0, v[34:35]
	v_mbcnt_hi_u32_b32 v2, -1, v2
	v_lshlrev_b32_e32 v6, 10, v6
	v_lshlrev_b32_e32 v7, 2, v42
	v_lshl_add_u64 v[38:39], v[4:5], 0, s[4:5]
	v_and_b32_e32 v4, 64, v2
	v_add3_u32 v7, 0, v6, v7
	v_and_b32_e32 v6, 0x3f00, v164
	v_xor_b32_e32 v3, 8, v2
	v_add_u32_e32 v4, 64, v4
	v_add_u32_e32 v8, 0, v6
	v_and_b32_e32 v6, 8, v162
	s_lshl_b32 s4, s0, 13
	v_cmp_lt_i32_e64 s[0:1], v3, v4
	v_and_b32_e32 v9, 0xf0, v164
	v_cmp_eq_u32_e32 vcc, 0, v6
	v_and_b32_e32 v6, 28, v163
	v_cndmask_b32_e64 v2, v2, v3, s[0:1]
	v_add_u32_e32 v45, s4, v7
	v_lshrrev_b32_e32 v43, 4, v162
	v_lshlrev_b32_e32 v44, 2, v2
	s_lshl_b32 s8, s76, 3
	s_lshl_b32 s9, s3, 3
	s_lshl_b32 s10, s76, 5
	s_lshl_b32 s11, s3, 5
	s_mov_b32 s12, 0x40000
	v_add_u32_e32 v46, v8, v9
	v_mov_b32_e32 v47, 0x358637bd
	s_mov_b32 s13, 0x800000
	v_lshlrev_b32_e32 v40, 1, v6
	v_add_u32_e32 v48, 0x800, v45
	v_add_u32_e32 v49, 0x1000, v45
	v_add_u32_e32 v50, 0x1800, v45
	s_mov_b32 s14, s76
	s_branch .LBB0_619

; template <class EpiS>
; DI void sample_gemm(LAS unsigned char* lds, const bf16_t* A, const bf16_t* Bt, int nN, int K, const EpiS& E) {
;     const int tid = threadIdx.x, lane = tid & 63, w = __builtin_amdgcn_readfirstlane(tid >> 6), r32 = lane & 31, h = lane >> 5;
;     const int nunits = 16 * nN, kw = K >> 3, nk = kw >> 4;
;     for (int un = (int)blockIdx.x; un < nunits; un += (int)gridDim.x) {
;         const int rb = un & 3, wc = (un >> 2) & 3, pn = un >> 4;
;         const bf16_t* ap = A + (size_t)(MP + rb * 32 + r32) * K + w * kw + h * 8;
;         const bf16_t* b0p = Bt + (size_t)(pn * 256 + wc * 32 + r32) * K + w * kw + h * 8;
;         const bf16_t* b1p = b0p + (size_t)128 * K;
.LBB0_719:
	s_cmp_gt_i32 s2, 63
	v_readfirstlane_b32 s0, v189
	s_cbranch_scc1 .LBB0_724
	v_and_b32_e32 v155, 63, v189
	v_lshrrev_b32_e32 v156, 6, v189
	v_and_b32_e32 v156, 7, v156
	v_lshlrev_b32_e32 v156, 13, v156
	v_add_u32_e32 v156, 0x10000, v156
	v_lshrrev_b32_e32 v182, 2, v155
	v_and_b32_e32 v165, 31, v155
	v_sub_u32_e32 v182, v182, v165
	v_mul_i32_i24_e32 v182, 0x1600, v182
	v_and_b32_e32 v165, 3, v155
	v_lshrrev_b32_e32 v183, 5, v155
	v_sub_u32_e32 v165, v165, v183
	v_lshl_add_u32 v182, v165, 4, v182
	v_ashrrev_i32_e32 v183, 31, v182
	v_lshrrev_b32_e32 v194, 4, v155
	v_xor_b32_e32 v194, v194, v155
	v_and_b32_e32 v194, 3, v194
	v_lshlrev_b32_e32 v194, 4, v194
	v_lshrrev_b32_e32 v165, 2, v155
	v_lshl_add_u32 v194, v165, 6, v194
	v_add_u32_e32 v194, v156, v194
	v_and_b32_e32 v165, 31, v155
	v_lshl_add_u32 v156, v165, 6, v156
	v_lshrrev_b32_e32 v165, 2, v155
	v_and_b32_e32 v165, 3, v165
	v_lshrrev_b32_e32 v155, 5, v155
	v_add_u32_e32 v244, 0, v155
	v_xor_b32_e32 v244, v244, v165
	v_lshl_add_u32 v244, v244, 4, v156
	v_add_u32_e32 v245, 2, v155
	v_xor_b32_e32 v245, v245, v165
	v_lshl_add_u32 v245, v245, 4, v156
	s_mov_b32 s80, 0x16000
	s_mov_b32 s81, 0
	s_and_b32 s76, s2, 0xffffffe0
	s_and_b32 s77, s2, 7
	s_lshl_b32 s77, s77, 2
	s_or_b32 s76, s76, s77
	s_bfe_u32 s77, s2, 0x20003
	s_or_b32 s76, s76, s77
	s_and_b32 s77, s3, 31
	s_cmp_eq_u32 s77, 0
	s_cselect_b32 s76, s76, s2
	s_lshr_b32 s6, s0, 6
	s_mul_i32 s0, s6, 0x160
	s_mov_b32 s1, 0
	s_lshl_b64 s[0:1], s[0:1], 1
	s_add_u32 s4, s24, s0
	s_addc_u32 s5, s25, s1
	v_bfe_u32 v2, v189, 5, 1
	s_add_u32 s0, s33, s0
	v_lshlrev_b32_e32 v34, 4, v2
	v_mov_b32_e32 v35, 0
	s_addc_u32 s1, s56, s1
	v_and_b32_e32 v40, 31, v189
	v_lshl_add_u64 v[38:39], s[0:1], 0, v[34:35]
	s_lshl_b32 s0, s6, 13
	s_add_i32 s0, s0, 0
	v_lshlrev_b32_e32 v2, 10, v2
	s_waitcnt lgkmcnt(0)
	v_lshlrev_b32_e32 v3, 2, v40
	v_add3_u32 v41, s0, v2, v3
	v_and_b32_e32 v4, 28, v192
	s_movk_i32 s0, 0x80
	v_and_or_b32 v42, v191, s0, v4
	v_mbcnt_lo_u32_b32 v4, -1, 0
	v_mbcnt_hi_u32_b32 v4, -1, v4
	v_and_b32_e32 v6, 64, v4
	v_xor_b32_e32 v5, 1, v4
	v_add_u32_e32 v6, 64, v6
	v_cmp_lt_i32_e32 vcc, v5, v6
	v_and_b32_e32 v2, 0x3f00, v191
	v_add_u32_e32 v2, 0, v2
	v_cndmask_b32_e32 v5, v4, v5, vcc
	v_lshlrev_b32_e32 v43, 2, v5
	v_xor_b32_e32 v5, 2, v4
	v_cmp_lt_i32_e32 vcc, v5, v6
	v_and_b32_e32 v3, 0xf0, v191
	v_lshl_add_u64 v[36:37], s[4:5], 0, v[34:35]
	v_cndmask_b32_e32 v5, v4, v5, vcc
	v_lshlrev_b32_e32 v44, 2, v5
	v_xor_b32_e32 v5, 4, v4
	v_cmp_lt_i32_e32 vcc, v5, v6
	s_lshl_b32 s4, s76, 3
	s_lshl_b32 s5, s3, 3
	v_cndmask_b32_e32 v5, v4, v5, vcc
	v_lshlrev_b32_e32 v45, 2, v5
	v_xor_b32_e32 v5, 8, v4
	v_cmp_lt_i32_e32 vcc, v5, v6
	s_lshl_b32 s6, s76, 4
	s_lshl_b32 s7, s3, 4
	v_cndmask_b32_e32 v4, v4, v5, vcc
	v_lshlrev_b32_e32 v46, 2, v4
	v_cmp_eq_u32_e32 vcc, 0, v190
	s_lshl_b32 s12, s76, 5
	s_lshl_b32 s13, s3, 5
	s_movk_i32 s14, 0x1600
	s_mov_b32 s15, 0xb0000
	v_add_u32_e32 v47, v2, v3
	v_add_u32_e32 v48, 0x800, v41
	v_add_u32_e32 v49, 0x1000, v41
	v_add_u32_e32 v50, 0x1800, v41
	s_mov_b32 s16, s76
	s_branch .LBB0_722

; template <class EpiS>
; DI void sample_gemm(LAS unsigned char* lds, const bf16_t* A, const bf16_t* Bt, int nN, int K, const EpiS& E) {
;     const int tid = threadIdx.x, lane = tid & 63, w = __builtin_amdgcn_readfirstlane(tid >> 6), r32 = lane & 31, h = lane >> 5;
;     const int nunits = 16 * nN, kw = K >> 3, nk = kw >> 4;
;     for (int un = (int)blockIdx.x; un < nunits; un += (int)gridDim.x) {
;         const int rb = un & 3, wc = (un >> 2) & 3, pn = un >> 4;
;         const bf16_t* ap = A + (size_t)(MP + rb * 32 + r32) * K + w * kw + h * 8;
;         const bf16_t* b0p = Bt + (size_t)(pn * 256 + wc * 32 + r32) * K + w * kw + h * 8;
;         const bf16_t* b1p = b0p + (size_t)128 * K;
.LBB0_932:
	s_cmpk_gt_i32 s2, 0x9f
	v_readfirstlane_b32 s4, v210
	s_cbranch_scc1 .LBB0_947
	v_and_b32_e32 v155, 63, v210
	v_lshrrev_b32_e32 v156, 6, v210
	v_and_b32_e32 v156, 7, v156
	v_lshlrev_b32_e32 v156, 13, v156
	v_add_u32_e32 v156, 0x10000, v156
	v_lshrrev_b32_e32 v182, 3, v155
	v_and_b32_e32 v165, 31, v155
	v_sub_u32_e32 v182, v182, v165
	v_lshlrev_b32_e32 v182, 11, v182
	v_and_b32_e32 v165, 7, v155
	v_lshrrev_b32_e32 v183, 5, v155
	v_sub_u32_e32 v165, v165, v183
	v_lshl_add_u32 v182, v165, 4, v182
	v_ashrrev_i32_e32 v183, 31, v182
	v_lshrrev_b32_e32 v194, 4, v155
	v_and_b32_e32 v194, 3, v194
	v_and_b32_e32 v165, 7, v155
	v_xor_b32_e32 v194, v194, v165
	v_lshlrev_b32_e32 v194, 4, v194
	v_lshrrev_b32_e32 v165, 3, v155
	v_lshl_add_u32 v194, v165, 7, v194
	v_add_u32_e32 v194, v156, v194
	v_xor_b32_e32 v195, 64, v194
	v_and_b32_e32 v165, 31, v155
	v_lshl_add_u32 v156, v165, 7, v156
	v_lshrrev_b32_e32 v165, 1, v155
	v_and_b32_e32 v165, 7, v165
	v_lshrrev_b32_e32 v155, 5, v155
	v_add_u32_e32 v244, 0, v155
	v_xor_b32_e32 v244, v244, v165
	v_lshl_add_u32 v244, v244, 4, v156
	v_add_u32_e32 v245, 2, v155
	v_xor_b32_e32 v245, v245, v165
	v_lshl_add_u32 v245, v245, 4, v156
	v_add_u32_e32 v246, 4, v155
	v_xor_b32_e32 v246, v246, v165
	v_lshl_add_u32 v246, v246, 4, v156
	v_add_u32_e32 v193, 6, v155
	v_xor_b32_e32 v193, v193, v165
	v_lshl_add_u32 v193, v193, 4, v156
	s_mov_b32 s80, 0x4000
	s_mov_b32 s81, 0
	s_mov_b32 s82, 0xffff4000
	s_mov_b32 s83, -1
	s_and_b32 s76, s2, 0xffffffe0
	s_and_b32 s77, s2, 7
	s_lshl_b32 s77, s77, 2
	s_or_b32 s76, s76, s77
	s_bfe_u32 s77, s2, 0x20003
	s_or_b32 s76, s76, s77
	s_and_b32 s77, s3, 31
	s_cmp_eq_u32 s77, 0
	s_cselect_b32 s76, s76, s2
	v_and_b32_e32 v6, 1, v215
	v_and_b32_e32 v37, 31, v210
	v_lshlrev_b32_e32 v34, 4, v6
	v_mov_b32_e32 v35, 0
	s_lshr_b32 s6, s4, 6
	s_mov_b32 s5, 0
	v_lshl_add_u64 v[2:3], s[34:35], 0, v[34:35]
	v_lshl_add_u64 v[4:5], s[18:19], 0, v[34:35]
	v_lshlrev_b32_e32 v6, 10, v6
	v_lshlrev_b32_e32 v7, 2, v37
	s_lshl_b32 s4, s6, 8
	v_add3_u32 v6, 0, v6, v7
	v_and_b32_e32 v7, 0x3f00, v212
	v_lshl_add_u64 v[38:39], v[2:3], 0, s[4:5]
	v_lshl_add_u64 v[40:41], v[4:5], 0, s[4:5]
	s_lshl_b32 s4, s6, 13
	v_add_u32_e32 v7, 0, v7
	v_and_b32_e32 v8, 0xf0, v212
	v_and_b32_e32 v9, 1, v213
	v_and_b32_e32 v42, 28, v214
	v_add_u32_e32 v44, s4, v6
	v_mbcnt_lo_u32_b32 v2, -1, 0
	v_lshlrev_b32_e32 v43, 7, v9
	v_cmp_eq_u32_e64 s[0:1], 0, v211
	v_lshl_or_b32 v36, v9, 5, v42
	s_lshl_b32 s10, s76, 5
	s_lshl_b32 s11, s3, 5
	s_mov_b32 s12, 0x40000
	v_add_u32_e32 v45, v7, v8
	v_mov_b32_e32 v46, 0x358637bd
	s_mov_b32 s13, 0x800000
	v_add_u32_e32 v47, 0x800, v44
	v_add_u32_e32 v48, 0x1000, v44
	v_add_u32_e32 v49, 0x1800, v44
	v_mbcnt_hi_u32_b32 v50, -1, v2
	v_mov_b32_e32 v51, 0x3e38aa3b
	s_mov_b32 s14, s76
	s_branch .LBB0_935

; template <class EpiS>
; DI void sample_gemm(LAS unsigned char* lds, const bf16_t* A, const bf16_t* Bt, int nN, int K, const EpiS& E) {
;     const int tid = threadIdx.x, lane = tid & 63, w = __builtin_amdgcn_readfirstlane(tid >> 6), r32 = lane & 31, h = lane >> 5;
;     const int nunits = 16 * nN, kw = K >> 3, nk = kw >> 4;
;     for (int un = (int)blockIdx.x; un < nunits; un += (int)gridDim.x) {
;         const int rb = un & 3, wc = (un >> 2) & 3, pn = un >> 4;
;         const bf16_t* ap = A + (size_t)(MP + rb * 32 + r32) * K + w * kw + h * 8;
;         const bf16_t* b0p = Bt + (size_t)(pn * 256 + wc * 32 + r32) * K + w * kw + h * 8;
;         const bf16_t* b1p = b0p + (size_t)128 * K;
.LBB0_1362:
	s_cmp_gt_i32 s2, 63
	v_readfirstlane_b32 s0, v189
	s_cbranch_scc1 .LBB0_1367
	v_and_b32_e32 v155, 63, v189
	v_lshrrev_b32_e32 v156, 6, v189
	v_and_b32_e32 v156, 7, v156
	v_lshlrev_b32_e32 v156, 13, v156
	v_add_u32_e32 v156, 0x10000, v156
	v_lshrrev_b32_e32 v182, 3, v155
	v_and_b32_e32 v165, 31, v155
	v_sub_u32_e32 v182, v182, v165
	v_lshlrev_b32_e32 v182, 11, v182
	v_and_b32_e32 v165, 7, v155
	v_lshrrev_b32_e32 v183, 5, v155
	v_sub_u32_e32 v165, v165, v183
	v_lshl_add_u32 v182, v165, 4, v182
	v_ashrrev_i32_e32 v183, 31, v182
	v_lshrrev_b32_e32 v194, 4, v155
	v_and_b32_e32 v194, 3, v194
	v_and_b32_e32 v165, 7, v155
	v_xor_b32_e32 v194, v194, v165
	v_lshlrev_b32_e32 v194, 4, v194
	v_lshrrev_b32_e32 v165, 3, v155
	v_lshl_add_u32 v194, v165, 7, v194
	v_add_u32_e32 v194, v156, v194
	v_xor_b32_e32 v195, 64, v194
	v_and_b32_e32 v165, 31, v155
	v_lshl_add_u32 v156, v165, 7, v156
	v_lshrrev_b32_e32 v165, 1, v155
	v_and_b32_e32 v165, 7, v165
	v_lshrrev_b32_e32 v155, 5, v155
	v_add_u32_e32 v244, 0, v155
	v_xor_b32_e32 v244, v244, v165
	v_lshl_add_u32 v244, v244, 4, v156
	v_add_u32_e32 v245, 2, v155
	v_xor_b32_e32 v245, v245, v165
	v_lshl_add_u32 v245, v245, 4, v156
	v_add_u32_e32 v246, 4, v155
	v_xor_b32_e32 v246, v246, v165
	v_lshl_add_u32 v246, v246, 4, v156
	v_add_u32_e32 v193, 6, v155
	v_xor_b32_e32 v193, v193, v165
	v_lshl_add_u32 v193, v193, 4, v156
	s_mov_b32 s80, 0x4000
	s_mov_b32 s81, 0
	s_mov_b32 s82, 0xffff4000
	s_mov_b32 s83, -1
	s_and_b32 s76, s2, 0xffffffe0
	s_and_b32 s77, s2, 7
	s_lshl_b32 s77, s77, 2
	s_or_b32 s76, s76, s77
	s_bfe_u32 s77, s2, 0x20003
	s_or_b32 s76, s76, s77
	s_and_b32 s77, s3, 31
	s_cmp_eq_u32 s77, 0
	s_cselect_b32 s76, s76, s2
	s_lshr_b32 s4, s0, 6
	s_lshl_b32 s5, s4, 8
	v_bfe_u32 v2, v189, 5, 1
	s_add_u32 s0, s26, s5
	s_addc_u32 s1, s27, 0
	v_lshlrev_b32_e32 v34, 4, v2
	v_mov_b32_e32 v35, 0
	v_lshl_add_u64 v[36:37], s[0:1], 0, v[34:35]
	s_add_u32 s0, s33, s5
	s_addc_u32 s1, s46, 0
	v_and_b32_e32 v40, 31, v189
	v_lshl_add_u64 v[38:39], s[0:1], 0, v[34:35]
	s_lshl_b32 s0, s4, 13
	s_add_i32 s0, s0, 0
	v_lshlrev_b32_e32 v2, 10, v2
	s_waitcnt lgkmcnt(0)
	v_lshlrev_b32_e32 v3, 2, v40
	v_add3_u32 v41, s0, v2, v3
	v_and_b32_e32 v4, 28, v192
	s_movk_i32 s0, 0x80
	v_and_or_b32 v42, v191, s0, v4
	v_mbcnt_lo_u32_b32 v4, -1, 0
	v_mbcnt_hi_u32_b32 v4, -1, v4
	v_and_b32_e32 v6, 64, v4
	v_xor_b32_e32 v5, 1, v4
	v_add_u32_e32 v6, 64, v6
	v_cmp_lt_i32_e32 vcc, v5, v6
	v_and_b32_e32 v2, 0x3f00, v191
	v_add_u32_e32 v2, 0, v2
	v_cndmask_b32_e32 v5, v4, v5, vcc
	v_lshlrev_b32_e32 v43, 2, v5
	v_xor_b32_e32 v5, 2, v4
	v_cmp_lt_i32_e32 vcc, v5, v6
	v_and_b32_e32 v3, 0xf0, v191
	s_lshl_b32 s4, s76, 3
	v_cndmask_b32_e32 v5, v4, v5, vcc
	v_lshlrev_b32_e32 v44, 2, v5
	v_xor_b32_e32 v5, 4, v4
	v_cmp_lt_i32_e32 vcc, v5, v6
	s_lshl_b32 s5, s3, 3
	s_lshl_b32 s10, s76, 4
	v_cndmask_b32_e32 v5, v4, v5, vcc
	v_lshlrev_b32_e32 v45, 2, v5
	v_xor_b32_e32 v5, 8, v4
	v_cmp_lt_i32_e32 vcc, v5, v6
	s_lshl_b32 s11, s3, 4
	s_lshl_b32 s12, s76, 5
	v_cndmask_b32_e32 v4, v4, v5, vcc
	v_lshlrev_b32_e32 v46, 2, v4
	v_cmp_eq_u32_e32 vcc, 0, v190
	s_lshl_b32 s13, s3, 5
	s_mov_b32 s14, 0x40000
	v_add_u32_e32 v47, v2, v3
	v_add_u32_e32 v48, 0x800, v41
	v_add_u32_e32 v49, 0x1000, v41
	v_add_u32_e32 v50, 0x1800, v41
	s_mov_b32 s15, s76
	s_branch .LBB0_1365

; template <class EpiS>
; DI void sample_gemm(LAS unsigned char* lds, const bf16_t* A, const bf16_t* Bt, int nN, int K, const EpiS& E) {
;     const int tid = threadIdx.x, lane = tid & 63, w = __builtin_amdgcn_readfirstlane(tid >> 6), r32 = lane & 31, h = lane >> 5;
;     const int nunits = 16 * nN, kw = K >> 3, nk = kw >> 4;
;     for (int un = (int)blockIdx.x; un < nunits; un += (int)gridDim.x) {
;         const int rb = un & 3, wc = (un >> 2) & 3, pn = un >> 4;
;         const bf16_t* ap = A + (size_t)(MP + rb * 32 + r32) * K + w * kw + h * 8;
;         const bf16_t* b0p = Bt + (size_t)(pn * 256 + wc * 32 + r32) * K + w * kw + h * 8;
;         const bf16_t* b1p = b0p + (size_t)128 * K;
.LBB0_1435:
	s_cmpk_gt_i32 s2, 0x15f
	v_readfirstlane_b32 s0, v162
	s_cbranch_scc1 .LBB0_1440
	v_and_b32_e32 v155, 63, v162
	v_lshrrev_b32_e32 v156, 6, v162
	v_and_b32_e32 v156, 7, v156
	v_lshlrev_b32_e32 v156, 13, v156
	v_add_u32_e32 v156, 0x10000, v156
	v_lshrrev_b32_e32 v182, 3, v155
	v_and_b32_e32 v165, 31, v155
	v_sub_u32_e32 v182, v182, v165
	v_lshlrev_b32_e32 v182, 11, v182
	v_and_b32_e32 v165, 7, v155
	v_lshrrev_b32_e32 v183, 5, v155
	v_sub_u32_e32 v165, v165, v183
	v_lshl_add_u32 v182, v165, 4, v182
	v_ashrrev_i32_e32 v183, 31, v182
	v_lshrrev_b32_e32 v194, 4, v155
	v_and_b32_e32 v194, 3, v194
	v_and_b32_e32 v165, 7, v155
	v_xor_b32_e32 v194, v194, v165
	v_lshlrev_b32_e32 v194, 4, v194
	v_lshrrev_b32_e32 v165, 3, v155
	v_lshl_add_u32 v194, v165, 7, v194
	v_add_u32_e32 v194, v156, v194
	v_xor_b32_e32 v195, 64, v194
	v_and_b32_e32 v165, 31, v155
	v_lshl_add_u32 v156, v165, 7, v156
	v_lshrrev_b32_e32 v165, 1, v155
	v_and_b32_e32 v165, 7, v165
	v_lshrrev_b32_e32 v155, 5, v155
	v_add_u32_e32 v244, 0, v155
	v_xor_b32_e32 v244, v244, v165
	v_lshl_add_u32 v244, v244, 4, v156
	v_add_u32_e32 v245, 2, v155
	v_xor_b32_e32 v245, v245, v165
	v_lshl_add_u32 v245, v245, 4, v156
	v_add_u32_e32 v246, 4, v155
	v_xor_b32_e32 v246, v246, v165
	v_lshl_add_u32 v246, v246, 4, v156
	v_add_u32_e32 v193, 6, v155
	v_xor_b32_e32 v193, v193, v165
	v_lshl_add_u32 v193, v193, 4, v156
	s_mov_b32 s80, 0x4000
	s_mov_b32 s81, 0
	s_mov_b32 s82, 0xffff4000
	s_mov_b32 s83, -1
	s_and_b32 s76, s2, 0xffffffe0
	s_and_b32 s77, s2, 7
	s_lshl_b32 s77, s77, 2
	s_or_b32 s76, s76, s77
	s_bfe_u32 s77, s2, 0x20003
	s_or_b32 s76, s76, s77
	s_and_b32 s77, s3, 31
	s_cmp_eq_u32 s77, 0
	s_cselect_b32 s76, s76, s2
	v_and_b32_e32 v1, 1, v1
	v_lshlrev_b32_e32 v34, 4, v1
	v_mov_b32_e32 v35, 0
	s_lshr_b32 s0, s0, 6
	s_mov_b32 s5, 0
	v_lshl_add_u64 v[2:3], s[34:35], 0, v[34:35]
	s_lshl_b32 s4, s0, 8
	v_lshl_add_u64 v[36:37], v[2:3], 0, s[4:5]
	v_mbcnt_lo_u32_b32 v2, -1, 0
	v_lshl_add_u64 v[4:5], s[22:23], 0, v[34:35]
	v_mbcnt_hi_u32_b32 v2, -1, v2
	v_and_b32_e32 v42, 31, v162
	v_lshl_add_u64 v[38:39], v[4:5], 0, s[4:5]
	v_and_b32_e32 v4, 64, v2
	v_lshlrev_b32_e32 v1, 10, v1
	v_lshlrev_b32_e32 v6, 2, v42
	v_xor_b32_e32 v3, 8, v2
	v_add_u32_e32 v4, 64, v4
	v_add3_u32 v7, 0, v1, v6
	v_and_b32_e32 v1, 0x3f00, v164
	s_lshl_b32 s4, s0, 13
	v_cmp_lt_i32_e64 s[0:1], v3, v4
	v_add_u32_e32 v8, 0, v1
	v_and_b32_e32 v9, 0xf0, v164
	v_and_b32_e32 v1, 8, v162
	v_and_b32_e32 v6, 28, v163
	v_cndmask_b32_e64 v2, v2, v3, s[0:1]
	v_add_u32_e32 v44, s4, v7
	v_cmp_eq_u32_e32 vcc, 0, v1
	v_lshrrev_b32_e32 v1, 4, v162
	v_lshlrev_b32_e32 v43, 2, v2
	s_lshl_b32 s8, s76, 3
	s_lshl_b32 s9, s3, 3
	s_lshl_b32 s10, s76, 5
	s_lshl_b32 s11, s3, 5
	s_mov_b32 s12, 0x40000
	v_add_u32_e32 v45, v8, v9
	v_mov_b32_e32 v46, 0x358637bd
	s_mov_b32 s13, 0x800000
	v_lshlrev_b32_e32 v40, 1, v6
	v_add_u32_e32 v47, 0x800, v44
	v_add_u32_e32 v48, 0x1000, v44
	v_add_u32_e32 v49, 0x1800, v44
	s_mov_b32 s14, s76
	s_branch .LBB0_1438

; template <class EpiS>
; DI void sample_gemm(LAS unsigned char* lds, const bf16_t* A, const bf16_t* Bt, int nN, int K, const EpiS& E) {
;     const int tid = threadIdx.x, lane = tid & 63, w = __builtin_amdgcn_readfirstlane(tid >> 6), r32 = lane & 31, h = lane >> 5;
;     const int nunits = 16 * nN, kw = K >> 3, nk = kw >> 4;
;     for (int un = (int)blockIdx.x; un < nunits; un += (int)gridDim.x) {
;         const int rb = un & 3, wc = (un >> 2) & 3, pn = un >> 4;
;         const bf16_t* ap = A + (size_t)(MP + rb * 32 + r32) * K + w * kw + h * 8;
;         const bf16_t* b0p = Bt + (size_t)(pn * 256 + wc * 32 + r32) * K + w * kw + h * 8;
;         const bf16_t* b1p = b0p + (size_t)128 * K;
.LBB0_1520:
	s_cmp_gt_i32 s2, 63
	v_readfirstlane_b32 s0, v153
	s_cbranch_scc1 .LBB0_1523
	v_and_b32_e32 v155, 63, v153
	v_lshrrev_b32_e32 v156, 6, v153
	v_and_b32_e32 v156, 7, v156
	v_lshlrev_b32_e32 v156, 13, v156
	v_add_u32_e32 v156, 0x10000, v156
	v_lshrrev_b32_e32 v182, 2, v155
	v_and_b32_e32 v165, 31, v155
	v_sub_u32_e32 v182, v182, v165
	v_mul_i32_i24_e32 v182, 0x1600, v182
	v_and_b32_e32 v165, 3, v155
	v_lshrrev_b32_e32 v183, 5, v155
	v_sub_u32_e32 v165, v165, v183
	v_lshl_add_u32 v182, v165, 4, v182
	v_ashrrev_i32_e32 v183, 31, v182
	v_lshrrev_b32_e32 v194, 4, v155
	v_xor_b32_e32 v194, v194, v155
	v_and_b32_e32 v194, 3, v194
	v_lshlrev_b32_e32 v194, 4, v194
	v_lshrrev_b32_e32 v165, 2, v155
	v_lshl_add_u32 v194, v165, 6, v194
	v_add_u32_e32 v194, v156, v194
	v_and_b32_e32 v165, 31, v155
	v_lshl_add_u32 v156, v165, 6, v156
	v_lshrrev_b32_e32 v165, 2, v155
	v_and_b32_e32 v165, 3, v165
	v_lshrrev_b32_e32 v155, 5, v155
	v_add_u32_e32 v244, 0, v155
	v_xor_b32_e32 v244, v244, v165
	v_lshl_add_u32 v244, v244, 4, v156
	v_add_u32_e32 v245, 2, v155
	v_xor_b32_e32 v245, v245, v165
	v_lshl_add_u32 v245, v245, 4, v156
	s_mov_b32 s80, 0x16000
	s_mov_b32 s81, 0
	s_and_b32 s76, s2, 0xffffffe0
	s_and_b32 s77, s2, 7
	s_lshl_b32 s77, s77, 2
	s_or_b32 s76, s76, s77
	s_bfe_u32 s77, s2, 0x20003
	s_or_b32 s76, s76, s77
	s_and_b32 s77, s3, 31
	s_cmp_eq_u32 s77, 0
	s_cselect_b32 s76, s76, s2
	s_mov_b32 s2, s76
	s_lshr_b32 s6, s0, 6
	s_mul_i32 s0, s6, 0x160
	s_mov_b32 s1, 0
	s_lshl_b64 s[0:1], s[0:1], 1
	s_add_u32 s4, s24, s0
	s_addc_u32 s5, s25, s1
	v_bfe_u32 v0, v153, 5, 1
	s_add_u32 s0, s20, s0
	v_lshlrev_b32_e32 v32, 4, v0
	v_mov_b32_e32 v33, 0
	s_addc_u32 s1, s21, s1
	v_and_b32_e32 v38, 31, v153
	v_lshl_add_u64 v[36:37], s[0:1], 0, v[32:33]
	s_lshl_b32 s0, s6, 13
	s_add_i32 s0, s0, 0
	v_lshlrev_b32_e32 v0, 10, v0
	v_lshlrev_b32_e32 v1, 2, v38
	v_add3_u32 v39, s0, v0, v1
	v_and_b32_e32 v0, 0x3f00, v152
	v_add_u32_e32 v0, 0, v0
	v_and_b32_e32 v1, 0xf0, v152
	v_and_b32_e32 v2, 28, v154
	s_movk_i32 s0, 0x80
	v_lshl_add_u64 v[34:35], s[4:5], 0, v[32:33]
	v_lshrrev_b32_e32 v40, 4, v153
	v_and_or_b32 v41, v152, s0, v2
	s_lshl_b32 s0, s76, 3
	s_lshl_b32 s1, s3, 3
	s_lshl_b32 s4, s76, 4
	s_lshl_b32 s5, s3, 4
	s_lshl_b32 s6, s76, 5
	s_lshl_b32 s7, s3, 5
	s_movk_i32 s8, 0x1600
	s_mov_b32 s9, 0xb0000
	v_add_u32_e32 v42, v0, v1
	v_add_u32_e32 v43, 0x800, v39
	v_add_u32_e32 v44, 0x1000, v39
	v_add_u32_e32 v45, 0x1800, v39
